# P8 residual epilogue: rs2 loads hoisted, waits no longer cover the write-through stores; sc1 epilogue stores; nt streamed-once loads; MLA role-split
# speedup vs baseline: 1.0109x; 1.0028x over previous
; __device__ __forceinline__ unsigned cvt_pk_bf16(float lo, float hi) { f32x2c_t v = {lo, hi}; bf16x2c_t b = __builtin_convertvector(v, bf16x2c_t); return __builtin_bit_cast(unsigned, b); }
; __device__ __forceinline__ f32x4 bf4_lo(u32x4 w) { return (f32x4){__uint_as_float(w.x << 16), __uint_as_float(w.x & 0xffff0000u), __uint_as_float(w.y << 16), __uint_as_float(w.y & 0xffff0000u)}; }
;     __device__ __forceinline__ void operator()(const f32x4 (&acc)[2][2][4][2], const Unit& u, int wr, int wc, int fr, int fq) const {
;     ...
;         const int row0 = u.pm * BM + wr * 64 + fr, col0 = u.pn * BM + wc * 32 + 8 * fq, b = u.pm >> 4;
;         f32x4 gv[2][2];
; #pragma unroll
;         for (int bj = 0; bj < 2; ++bj)
; #pragma unroll
;             for (int n = 0; n < 2; ++n) gv[bj][n] = *(const f32x4*)(gate + (size_t)b * NMODC + col0 + bj * HALF + n * 4) * (MIX ? 1.0f : 0.5f);
;         u32x4 xw[2][4][2];
;         if constexpr (!XF32) {
; #pragma unroll
;             for (int ai = 0; ai < 2; ++ai)
; #pragma unroll
;                 for (int m = 0; m < 4; ++m)
; #pragma unroll
;                     for (int bj = 0; bj < 2; ++bj) xw[ai][m][bj] = *(const u32x4*)((const bf16_t*)xin + (size_t)(row0 + ai * HALF + m * 16) * 1024 + col0 + bj * HALF);
;         }
; #pragma unroll
;         for (int ai = 0; ai < 2; ++ai)
; #pragma unroll
;             for (int m = 0; m < 4; ++m) { const int row = row0 + ai * HALF + m * 16; const size_t off = (size_t)row * 1024 + col0; float rs = 1.f; if constexpr (MIX) { const float* sp = rs2 + 4 * row + 2; rs = 1.0f / sqrtf((sp[0] + sp[1]) * (1.f / 512.f) + NEPS); }
; #pragma unroll
;                 for (int bj = 0; bj < 2; ++bj) { f32x4 x0, x1;
;                     if constexpr (XF32) { x0 = *(const f32x4*)((const float*)xin + off + bj * HALF); x1 = *(const f32x4*)((const float*)xin + off + bj * HALF + 4); }
;                     else { const u32x4 w = xw[ai][m][bj]; x0 = bf4_lo(w); x1 = bf4_hi(w); }
;                     const f32x4 o0 = x0 + gv[bj][0] * (acc[ai][bj][m][0] * rs), o1 = x1 + gv[bj][1] * (acc[ai][bj][m][1] * rs);
;                     u32x4 w; w.x = cvt_pk_bf16(o0[0], o0[1]); w.y = cvt_pk_bf16(o0[2], o0[3]); w.z = cvt_pk_bf16(o1[0], o1[1]); w.w = cvt_pk_bf16(o1[2], o1[3]);
;                     *(u32x4*)(xout + off + bj * HALF) = w; } }
.LBB0_903:
	s_lshl_b32 s6, s64, 8
	v_mov_b32_e32 v1, v168
	v_mov_b32_e32 v2, v169
	s_add_i32 s6, s6, s43
	s_lshl_b32 s7, s69, 8
	v_add_u32_e32 v166, s6, v1
	v_lshlrev_b32_e32 v122, 2, v166
	v_ashrrev_i32_e32 v123, 31, v122
	v_lshl_add_u64 v[122:123], v[122:123], 2, s[46:47]
	global_load_dwordx2 v[186:187], v[122:123], off offset:8
	global_load_dwordx2 v[212:213], v[122:123], off offset:264
	global_load_dwordx2 v[214:215], v[122:123], off offset:520
	global_load_dwordx2 v[216:217], v[122:123], off offset:776
	global_load_dwordx2 v[218:219], v[122:123], off offset:2056
	global_load_dwordx2 v[220:221], v[122:123], off offset:2312
	global_load_dwordx2 v[222:223], v[122:123], off offset:2568
	global_load_dwordx2 v[224:225], v[122:123], off offset:2824
	s_or_b32 s7, s7, s54
	v_lshl_add_u32 v120, v2, 3, s7
	v_ashrrev_i32_e32 v121, 31, v120
	s_ashr_i32 s6, s64, 4
	v_lshlrev_b64 v[2:3], 1, v[120:121]
	v_ashrrev_i32_e32 v167, 31, v166
	s_mul_hi_i32 s7, s6, 0x9000
	s_mul_i32 s6, s6, 0x9000
	v_lshl_add_u64 v[164:165], s[24:25], 0, v[2:3]
	v_lshlrev_b64 v[184:185], 11, v[166:167]
	s_add_u32 s6, s37, s6
	v_lshl_add_u64 v[122:123], v[164:165], 0, v[184:185]
	s_addc_u32 s7, s41, s7
	global_load_dwordx4 v[176:179], v[122:123], off
	global_load_dwordx4 v[180:183], v[122:123], off offset:256
	v_lshl_add_u64 v[120:121], v[120:121], 2, s[6:7]
	global_load_dwordx4 v[136:139], v[120:121], off
	global_load_dwordx4 v[132:135], v[120:121], off offset:16
	global_load_dwordx4 v[128:131], v[120:121], off offset:512
	s_nop 0
	global_load_dwordx4 v[120:123], v[120:121], off offset:528
	v_add_u32_e32 v190, 16, v166
	v_ashrrev_i32_e32 v191, 31, v190
	v_lshlrev_b32_e32 v192, 2, v190
	v_lshlrev_b64 v[198:199], 11, v[190:191]
	v_lshl_add_u64 v[184:185], s[24:25], 0, v[184:185]
	v_ashrrev_i32_e32 v193, 31, v192
	v_lshl_add_u64 v[194:195], v[164:165], 0, v[198:199]
	v_lshl_add_u64 v[184:185], v[184:185], 0, v[2:3]
	v_lshl_add_u64 v[200:201], v[192:193], 2, s[46:47]
	global_load_dwordx4 v[190:193], v[194:195], off
	s_nop 0
	global_load_dwordx4 v[194:197], v[194:195], off offset:256
	s_waitcnt vmcnt(0)
	v_add_f32_e32 v1, v186, v187
	v_fmamk_f32 v1, v1, 0x3b000000, v174
	v_mul_f32_e32 v167, 0x4f800000, v1
	v_cmp_gt_f32_e32 vcc, s61, v1
	v_lshlrev_b32_e32 v186, 16, v176
	s_nop 0
	v_cndmask_b32_e32 v1, v1, v167, vcc
	v_sqrt_f32_e32 v167, v1
	v_and_b32_e32 v187, 0xffff0000, v176
	v_lshlrev_b32_e32 v176, 16, v177
	v_and_b32_e32 v177, 0xffff0000, v177
	v_add_u32_e32 v175, -1, v167
	v_add_u32_e32 v208, 1, v167
	v_fma_f32 v209, -v175, v167, v1
	v_fma_f32 v210, -v208, v167, v1
	v_cmp_ge_f32_e64 s[6:7], 0, v209
	v_lshlrev_b32_e32 v202, 16, v178
	v_and_b32_e32 v203, 0xffff0000, v178
	v_cndmask_b32_e64 v167, v167, v175, s[6:7]
	v_cmp_lt_f32_e64 s[6:7], 0, v210
	v_lshlrev_b32_e32 v178, 16, v179
	v_and_b32_e32 v179, 0xffff0000, v179
	v_cndmask_b32_e64 v167, v167, v208, s[6:7]
	v_mul_f32_e32 v175, 0x37800000, v167
	v_cndmask_b32_e32 v167, v167, v175, vcc
	v_cmp_class_f32_e32 vcc, v1, v172
	v_lshlrev_b32_e32 v204, 16, v180
	v_and_b32_e32 v205, 0xffff0000, v180
	v_cndmask_b32_e32 v1, v167, v1, vcc
	v_div_scale_f32 v167, s[6:7], v1, v1, 1.0
	v_rcp_f32_e32 v175, v167
	v_div_scale_f32 v208, vcc, 1.0, v1, 1.0
	v_lshlrev_b32_e32 v180, 16, v181
	v_fma_f32 v209, -v167, v175, 1.0
	v_fmac_f32_e32 v175, v209, v175
	v_mul_f32_e32 v209, v208, v175
	v_fma_f32 v210, -v167, v209, v208
	v_fmac_f32_e32 v209, v210, v175
	v_fma_f32 v167, -v167, v209, v208
	v_div_fmas_f32 v167, v167, v175, v209
	v_div_fixup_f32 v208, v167, v1, 1.0
	v_pk_mul_f32 v[144:145], v[144:145], v[208:209] op_sel_hi:[1,0]
	v_pk_mul_f32 v[146:147], v[146:147], v[208:209] op_sel_hi:[1,0]
	v_pk_mul_f32 v[140:141], v[140:141], v[208:209] op_sel_hi:[1,0]
	v_pk_mul_f32 v[142:143], v[142:143], v[208:209] op_sel_hi:[1,0]
	v_and_b32_e32 v181, 0xffff0000, v181
	v_lshlrev_b32_e32 v206, 16, v182
	v_and_b32_e32 v207, 0xffff0000, v182
	v_lshlrev_b32_e32 v182, 16, v183
	v_and_b32_e32 v183, 0xffff0000, v183
	v_pk_mul_f32 v[124:125], v[124:125], v[208:209] op_sel_hi:[1,0]
	v_pk_mul_f32 v[126:127], v[126:127], v[208:209] op_sel_hi:[1,0]
	v_pk_mul_f32 v[116:117], v[116:117], v[208:209] op_sel_hi:[1,0]
	v_pk_mul_f32 v[118:119], v[118:119], v[208:209] op_sel_hi:[1,0]
	v_pk_fma_f32 v[146:147], v[138:139], v[146:147], v[176:177]
	v_pk_fma_f32 v[144:145], v[136:137], v[144:145], v[186:187]
	v_pk_fma_f32 v[142:143], v[134:135], v[142:143], v[178:179]
	v_pk_fma_f32 v[140:141], v[132:133], v[140:141], v[202:203]
	v_pk_fma_f32 v[126:127], v[130:131], v[126:127], v[180:181]
	v_pk_fma_f32 v[124:125], v[128:129], v[124:125], v[204:205]
	v_pk_fma_f32 v[176:177], v[122:123], v[118:119], v[182:183]
	v_pk_fma_f32 v[178:179], v[120:121], v[116:117], v[206:207]
	v_cvt_pk_bf16_f32 v116, v144, v145
	v_cvt_pk_bf16_f32 v117, v146, v147
	v_cvt_pk_bf16_f32 v118, v140, v141
	v_cvt_pk_bf16_f32 v119, v142, v143
	v_cvt_pk_bf16_f32 v124, v124, v125
	v_cvt_pk_bf16_f32 v125, v126, v127
	v_cvt_pk_bf16_f32 v126, v178, v179
	v_cvt_pk_bf16_f32 v127, v176, v177
	global_store_dwordx4 v[184:185], v[116:119], off sc1
	global_store_dwordx4 v[184:185], v[124:127], off offset:256 sc1
	v_lshlrev_b32_e32 v178, 16, v191
	v_and_b32_e32 v179, 0xffff0000, v191
	v_lshlrev_b32_e32 v180, 16, v192
	v_and_b32_e32 v181, 0xffff0000, v192
	v_lshlrev_b32_e32 v182, 16, v193
	v_and_b32_e32 v183, 0xffff0000, v193
	v_lshlrev_b32_e32 v184, 16, v194
	v_and_b32_e32 v185, 0xffff0000, v194
	v_add_u32_e32 v116, 32, v166
	v_ashrrev_i32_e32 v117, 31, v116
	v_lshlrev_b32_e32 v176, 16, v190
	v_and_b32_e32 v177, 0xffff0000, v190
	v_lshlrev_b32_e32 v118, 2, v116
	v_lshlrev_b64 v[142:143], 11, v[116:117]
	v_lshl_add_u64 v[144:145], s[24:25], 0, v[198:199]
	v_lshlrev_b32_e32 v186, 16, v195
	v_and_b32_e32 v187, 0xffff0000, v195
	v_lshlrev_b32_e32 v190, 16, v197
	v_ashrrev_i32_e32 v119, 31, v118
	v_lshl_add_u64 v[124:125], v[164:165], 0, v[142:143]
	v_lshl_add_u64 v[144:145], v[144:145], 0, v[2:3]
	v_lshl_add_u64 v[146:147], v[118:119], 2, s[46:47]
	global_load_dwordx4 v[116:119], v[124:125], off
	s_nop 0
	global_load_dwordx4 v[124:127], v[124:125], off offset:256
	s_waitcnt vmcnt(4)
; __device__ __forceinline__ unsigned cvt_pk_bf16(float lo, float hi) { f32x2c_t v = {lo, hi}; bf16x2c_t b = __builtin_convertvector(v, bf16x2c_t); return __builtin_bit_cast(unsigned, b); }
; __device__ __forceinline__ f32x4 bf4_lo(u32x4 w) { return (f32x4){__uint_as_float(w.x << 16), __uint_as_float(w.x & 0xffff0000u), __uint_as_float(w.y << 16), __uint_as_float(w.y & 0xffff0000u)}; }
; __device__ __forceinline__ f32x4 bf4_hi(u32x4 w) { return (f32x4){__uint_as_float(w.z << 16), __uint_as_float(w.z & 0xffff0000u), __uint_as_float(w.w << 16), __uint_as_float(w.w & 0xffff0000u)}; }
;     __device__ __forceinline__ void operator()(const f32x4 (&acc)[2][2][4][2], const Unit& u, int wr, int wc, int fr, int fq) const {
;     ...
;         for (int ai = 0; ai < 2; ++ai)
; #pragma unroll
;             for (int m = 0; m < 4; ++m) { const int row = row0 + ai * HALF + m * 16; const size_t off = (size_t)row * 1024 + col0; float rs = 1.f; if constexpr (MIX) { const float* sp = rs2 + 4 * row + 2; rs = 1.0f / sqrtf((sp[0] + sp[1]) * (1.f / 512.f) + NEPS); }
; #pragma unroll
;                 for (int bj = 0; bj < 2; ++bj) { f32x4 x0, x1;
;                     if constexpr (XF32) { x0 = *(const f32x4*)((const float*)xin + off + bj * HALF); x1 = *(const f32x4*)((const float*)xin + off + bj * HALF + 4); }
;                     else { const u32x4 w = xw[ai][m][bj]; x0 = bf4_lo(w); x1 = bf4_hi(w); }
;                     const f32x4 o0 = x0 + gv[bj][0] * (acc[ai][bj][m][0] * rs), o1 = x1 + gv[bj][1] * (acc[ai][bj][m][1] * rs);
;                     u32x4 w; w.x = cvt_pk_bf16(o0[0], o0[1]); w.y = cvt_pk_bf16(o0[2], o0[3]); w.z = cvt_pk_bf16(o1[0], o1[1]); w.w = cvt_pk_bf16(o1[2], o1[3]);
;                     *(u32x4*)(xout + off + bj * HALF) = w; } }
	v_add_f32_e32 v1, v212, v213
	v_fmamk_f32 v1, v1, 0x3b000000, v174
	v_mul_f32_e32 v140, 0x4f800000, v1
	v_cmp_gt_f32_e32 vcc, s61, v1
	v_and_b32_e32 v141, 0xffff0000, v196
	s_nop 0
	v_cndmask_b32_e32 v1, v1, v140, vcc
	v_sqrt_f32_e32 v167, v1
	v_lshlrev_b32_e32 v140, 16, v196
	v_add_u32_e32 v175, -1, v167
	v_add_u32_e32 v191, 1, v167
	v_fma_f32 v192, -v175, v167, v1
	v_fma_f32 v193, -v191, v167, v1
	v_cmp_ge_f32_e64 s[6:7], 0, v192
	s_nop 1
	v_cndmask_b32_e64 v167, v167, v175, s[6:7]
	v_cmp_lt_f32_e64 s[6:7], 0, v193
	s_nop 1
	v_cndmask_b32_e64 v167, v167, v191, s[6:7]
	v_mul_f32_e32 v175, 0x37800000, v167
	v_cndmask_b32_e32 v167, v167, v175, vcc
	v_cmp_class_f32_e32 vcc, v1, v172
	v_and_b32_e32 v191, 0xffff0000, v197
	s_nop 0
	v_cndmask_b32_e32 v1, v167, v1, vcc
	v_div_scale_f32 v167, s[6:7], v1, v1, 1.0
	v_rcp_f32_e32 v175, v167
	v_div_scale_f32 v192, vcc, 1.0, v1, 1.0
	v_fma_f32 v193, -v167, v175, 1.0
	v_fmac_f32_e32 v175, v193, v175
	v_mul_f32_e32 v193, v192, v175
	v_fma_f32 v194, -v167, v193, v192
	v_fmac_f32_e32 v193, v194, v175
	v_fma_f32 v167, -v167, v193, v192
	v_div_fmas_f32 v167, v167, v175, v193
	v_div_fixup_f32 v192, v167, v1, 1.0
	v_pk_mul_f32 v[112:113], v[112:113], v[192:193] op_sel_hi:[1,0]
	v_pk_mul_f32 v[114:115], v[114:115], v[192:193] op_sel_hi:[1,0]
	v_pk_mul_f32 v[108:109], v[108:109], v[192:193] op_sel_hi:[1,0]
	v_pk_mul_f32 v[110:111], v[110:111], v[192:193] op_sel_hi:[1,0]
	v_pk_mul_f32 v[104:105], v[104:105], v[192:193] op_sel_hi:[1,0]
	v_pk_mul_f32 v[106:107], v[106:107], v[192:193] op_sel_hi:[1,0]
	v_pk_mul_f32 v[100:101], v[100:101], v[192:193] op_sel_hi:[1,0]
	v_pk_mul_f32 v[102:103], v[102:103], v[192:193] op_sel_hi:[1,0]
	v_pk_fma_f32 v[114:115], v[138:139], v[114:115], v[178:179]
	v_pk_fma_f32 v[112:113], v[136:137], v[112:113], v[176:177]
	v_pk_fma_f32 v[110:111], v[134:135], v[110:111], v[182:183]
	v_pk_fma_f32 v[108:109], v[132:133], v[108:109], v[180:181]
	v_pk_fma_f32 v[106:107], v[130:131], v[106:107], v[186:187]
	v_pk_fma_f32 v[104:105], v[128:129], v[104:105], v[184:185]
	v_pk_fma_f32 v[176:177], v[122:123], v[102:103], v[190:191]
	v_pk_fma_f32 v[140:141], v[120:121], v[100:101], v[140:141]
	v_cvt_pk_bf16_f32 v100, v112, v113
	v_cvt_pk_bf16_f32 v101, v114, v115
	v_cvt_pk_bf16_f32 v102, v108, v109
	v_cvt_pk_bf16_f32 v103, v110, v111
	v_cvt_pk_bf16_f32 v104, v104, v105
	v_cvt_pk_bf16_f32 v105, v106, v107
	v_cvt_pk_bf16_f32 v106, v140, v141
	v_cvt_pk_bf16_f32 v107, v176, v177
	global_store_dwordx4 v[144:145], v[100:103], off sc1
	global_store_dwordx4 v[144:145], v[104:107], off offset:256 sc1
	v_add_u32_e32 v100, 48, v166
	v_ashrrev_i32_e32 v101, 31, v100
	v_lshl_add_u64 v[112:113], s[24:25], 0, v[142:143]
	s_waitcnt vmcnt(3)
	v_lshlrev_b32_e32 v140, 16, v116
	v_and_b32_e32 v141, 0xffff0000, v116
	v_lshlrev_b32_e32 v116, 16, v117
	v_and_b32_e32 v117, 0xffff0000, v117
	v_lshlrev_b32_e32 v142, 16, v118
	v_and_b32_e32 v143, 0xffff0000, v118
	v_lshlrev_b32_e32 v118, 16, v119
	v_and_b32_e32 v119, 0xffff0000, v119
	v_lshlrev_b32_e32 v102, 2, v100
	v_lshlrev_b64 v[110:111], 11, v[100:101]
	s_waitcnt vmcnt(2)
	v_lshlrev_b32_e32 v144, 16, v124
	v_and_b32_e32 v145, 0xffff0000, v124
	v_lshlrev_b32_e32 v124, 16, v125
	v_and_b32_e32 v125, 0xffff0000, v125
	v_ashrrev_i32_e32 v103, 31, v102
	v_lshl_add_u64 v[104:105], v[164:165], 0, v[110:111]
	v_lshl_add_u64 v[112:113], v[112:113], 0, v[2:3]
	v_lshl_add_u64 v[114:115], v[102:103], 2, s[46:47]
	global_load_dwordx4 v[100:103], v[104:105], off
	s_nop 0
	global_load_dwordx4 v[104:107], v[104:105], off offset:256
	s_waitcnt vmcnt(4)
	v_add_f32_e32 v1, v214, v215
	v_fmamk_f32 v1, v1, 0x3b000000, v174
	v_mul_f32_e32 v108, 0x4f800000, v1
	v_cmp_gt_f32_e32 vcc, s61, v1
	v_and_b32_e32 v109, 0xffff0000, v126
	s_nop 0
	v_cndmask_b32_e32 v1, v1, v108, vcc
	v_sqrt_f32_e32 v146, v1
	v_lshlrev_b32_e32 v108, 16, v126
	v_lshlrev_b32_e32 v126, 16, v127
	v_and_b32_e32 v127, 0xffff0000, v127
	v_add_u32_e32 v147, -1, v146
	v_add_u32_e32 v167, 1, v146
	v_fma_f32 v175, -v147, v146, v1
	v_fma_f32 v176, -v167, v146, v1
	v_cmp_ge_f32_e64 s[6:7], 0, v175
	s_nop 1
	v_cndmask_b32_e64 v146, v146, v147, s[6:7]
	v_cmp_lt_f32_e64 s[6:7], 0, v176
	s_nop 1
	v_cndmask_b32_e64 v146, v146, v167, s[6:7]
	v_mul_f32_e32 v147, 0x37800000, v146
	v_cndmask_b32_e32 v146, v146, v147, vcc
	v_cmp_class_f32_e32 vcc, v1, v172
	s_nop 1
	v_cndmask_b32_e32 v1, v146, v1, vcc
	v_div_scale_f32 v146, s[6:7], v1, v1, 1.0
	v_rcp_f32_e32 v147, v146
	v_div_scale_f32 v167, vcc, 1.0, v1, 1.0
	v_fma_f32 v175, -v146, v147, 1.0
	v_fmac_f32_e32 v147, v175, v147
	v_mul_f32_e32 v175, v167, v147
	v_fma_f32 v176, -v146, v175, v167
	v_fmac_f32_e32 v175, v176, v147
	v_fma_f32 v146, -v146, v175, v167
	v_div_fmas_f32 v146, v146, v147, v175
	v_div_fixup_f32 v146, v146, v1, 1.0
	v_pk_mul_f32 v[96:97], v[96:97], v[146:147] op_sel_hi:[1,0]
	v_pk_mul_f32 v[98:99], v[98:99], v[146:147] op_sel_hi:[1,0]
	v_pk_mul_f32 v[92:93], v[92:93], v[146:147] op_sel_hi:[1,0]
	v_pk_mul_f32 v[94:95], v[94:95], v[146:147] op_sel_hi:[1,0]
	v_pk_mul_f32 v[88:89], v[88:89], v[146:147] op_sel_hi:[1,0]
	v_pk_mul_f32 v[90:91], v[90:91], v[146:147] op_sel_hi:[1,0]
	v_pk_mul_f32 v[84:85], v[84:85], v[146:147] op_sel_hi:[1,0]
	v_pk_mul_f32 v[86:87], v[86:87], v[146:147] op_sel_hi:[1,0]
	v_pk_fma_f32 v[98:99], v[138:139], v[98:99], v[116:117]
	v_pk_fma_f32 v[96:97], v[136:137], v[96:97], v[140:141]
	v_pk_fma_f32 v[94:95], v[134:135], v[94:95], v[118:119]
	v_pk_fma_f32 v[92:93], v[132:133], v[92:93], v[142:143]
	v_pk_fma_f32 v[90:91], v[130:131], v[90:91], v[124:125]
	v_pk_fma_f32 v[88:89], v[128:129], v[88:89], v[144:145]
	v_pk_fma_f32 v[116:117], v[122:123], v[86:87], v[126:127]
	v_pk_fma_f32 v[108:109], v[120:121], v[84:85], v[108:109]
	v_cvt_pk_bf16_f32 v84, v96, v97
	v_cvt_pk_bf16_f32 v85, v98, v99
	v_cvt_pk_bf16_f32 v86, v92, v93
	v_cvt_pk_bf16_f32 v87, v94, v95
	v_cvt_pk_bf16_f32 v88, v88, v89
	v_cvt_pk_bf16_f32 v89, v90, v91
	v_cvt_pk_bf16_f32 v90, v108, v109
	v_cvt_pk_bf16_f32 v91, v116, v117
	global_store_dwordx4 v[112:113], v[84:87], off sc1
	global_store_dwordx4 v[112:113], v[88:91], off offset:256 sc1
	v_add_u32_e32 v84, 0x80, v166
	v_ashrrev_i32_e32 v85, 31, v84
	v_lshl_add_u64 v[96:97], s[24:25], 0, v[110:111]
	s_waitcnt vmcnt(3)
; __device__ __forceinline__ unsigned cvt_pk_bf16(float lo, float hi) { f32x2c_t v = {lo, hi}; bf16x2c_t b = __builtin_convertvector(v, bf16x2c_t); return __builtin_bit_cast(unsigned, b); }
; __device__ __forceinline__ f32x4 bf4_lo(u32x4 w) { return (f32x4){__uint_as_float(w.x << 16), __uint_as_float(w.x & 0xffff0000u), __uint_as_float(w.y << 16), __uint_as_float(w.y & 0xffff0000u)}; }
; __device__ __forceinline__ f32x4 bf4_hi(u32x4 w) { return (f32x4){__uint_as_float(w.z << 16), __uint_as_float(w.z & 0xffff0000u), __uint_as_float(w.w << 16), __uint_as_float(w.w & 0xffff0000u)}; }
;     __device__ __forceinline__ void operator()(const f32x4 (&acc)[2][2][4][2], const Unit& u, int wr, int wc, int fr, int fq) const {
;     ...
;         for (int ai = 0; ai < 2; ++ai)
; #pragma unroll
;             for (int m = 0; m < 4; ++m) { const int row = row0 + ai * HALF + m * 16; const size_t off = (size_t)row * 1024 + col0; float rs = 1.f; if constexpr (MIX) { const float* sp = rs2 + 4 * row + 2; rs = 1.0f / sqrtf((sp[0] + sp[1]) * (1.f / 512.f) + NEPS); }
; #pragma unroll
;                 for (int bj = 0; bj < 2; ++bj) { f32x4 x0, x1;
;                     if constexpr (XF32) { x0 = *(const f32x4*)((const float*)xin + off + bj * HALF); x1 = *(const f32x4*)((const float*)xin + off + bj * HALF + 4); }
;                     else { const u32x4 w = xw[ai][m][bj]; x0 = bf4_lo(w); x1 = bf4_hi(w); }
;                     const f32x4 o0 = x0 + gv[bj][0] * (acc[ai][bj][m][0] * rs), o1 = x1 + gv[bj][1] * (acc[ai][bj][m][1] * rs);
;                     u32x4 w; w.x = cvt_pk_bf16(o0[0], o0[1]); w.y = cvt_pk_bf16(o0[2], o0[3]); w.z = cvt_pk_bf16(o1[0], o1[1]); w.w = cvt_pk_bf16(o1[2], o1[3]);
;                     *(u32x4*)(xout + off + bj * HALF) = w; } }
	v_lshlrev_b32_e32 v108, 16, v100
	v_and_b32_e32 v109, 0xffff0000, v100
	v_lshlrev_b32_e32 v100, 16, v101
	v_and_b32_e32 v101, 0xffff0000, v101
	v_lshlrev_b32_e32 v110, 16, v102
	v_and_b32_e32 v111, 0xffff0000, v102
	v_lshlrev_b32_e32 v102, 16, v103
	v_and_b32_e32 v103, 0xffff0000, v103
	v_lshlrev_b32_e32 v86, 2, v84
	v_lshlrev_b64 v[94:95], 11, v[84:85]
	s_waitcnt vmcnt(2)
	v_lshlrev_b32_e32 v112, 16, v104
	v_and_b32_e32 v113, 0xffff0000, v104
	v_lshlrev_b32_e32 v104, 16, v105
	v_and_b32_e32 v105, 0xffff0000, v105
	v_ashrrev_i32_e32 v87, 31, v86
	v_lshl_add_u64 v[88:89], v[164:165], 0, v[94:95]
	v_lshl_add_u64 v[96:97], v[96:97], 0, v[2:3]
	v_lshl_add_u64 v[98:99], v[86:87], 2, s[46:47]
	global_load_dwordx4 v[84:87], v[88:89], off
	s_nop 0
	global_load_dwordx4 v[88:91], v[88:89], off offset:256
	s_waitcnt vmcnt(4)
	v_add_f32_e32 v1, v216, v217
	v_fmamk_f32 v1, v1, 0x3b000000, v174
	v_mul_f32_e32 v92, 0x4f800000, v1
	v_cmp_gt_f32_e32 vcc, s61, v1
	v_and_b32_e32 v93, 0xffff0000, v106
	s_nop 0
	v_cndmask_b32_e32 v1, v1, v92, vcc
	v_sqrt_f32_e32 v114, v1
	v_lshlrev_b32_e32 v92, 16, v106
	v_lshlrev_b32_e32 v106, 16, v107
	v_and_b32_e32 v107, 0xffff0000, v107
	v_add_u32_e32 v115, -1, v114
	v_add_u32_e32 v116, 1, v114
	v_fma_f32 v117, -v115, v114, v1
	v_fma_f32 v118, -v116, v114, v1
	v_cmp_ge_f32_e64 s[6:7], 0, v117
	s_nop 1
	v_cndmask_b32_e64 v114, v114, v115, s[6:7]
	v_cmp_lt_f32_e64 s[6:7], 0, v118
	s_nop 1
	v_cndmask_b32_e64 v114, v114, v116, s[6:7]
	v_mul_f32_e32 v115, 0x37800000, v114
	v_cndmask_b32_e32 v114, v114, v115, vcc
	v_cmp_class_f32_e32 vcc, v1, v172
	s_nop 1
	v_cndmask_b32_e32 v1, v114, v1, vcc
	v_div_scale_f32 v114, s[6:7], v1, v1, 1.0
	v_rcp_f32_e32 v115, v114
	v_div_scale_f32 v116, vcc, 1.0, v1, 1.0
	v_fma_f32 v117, -v114, v115, 1.0
	v_fmac_f32_e32 v115, v117, v115
	v_mul_f32_e32 v117, v116, v115
	v_fma_f32 v118, -v114, v117, v116
	v_fmac_f32_e32 v117, v118, v115
	v_fma_f32 v114, -v114, v117, v116
	v_div_fmas_f32 v114, v114, v115, v117
	v_div_fixup_f32 v114, v114, v1, 1.0
	v_pk_mul_f32 v[80:81], v[80:81], v[114:115] op_sel_hi:[1,0]
	v_pk_mul_f32 v[82:83], v[82:83], v[114:115] op_sel_hi:[1,0]
	v_pk_mul_f32 v[76:77], v[76:77], v[114:115] op_sel_hi:[1,0]
	v_pk_mul_f32 v[78:79], v[78:79], v[114:115] op_sel_hi:[1,0]
	v_pk_mul_f32 v[72:73], v[72:73], v[114:115] op_sel_hi:[1,0]
	v_pk_mul_f32 v[74:75], v[74:75], v[114:115] op_sel_hi:[1,0]
	v_pk_mul_f32 v[68:69], v[68:69], v[114:115] op_sel_hi:[1,0]
	v_pk_mul_f32 v[70:71], v[70:71], v[114:115] op_sel_hi:[1,0]
	v_pk_fma_f32 v[82:83], v[138:139], v[82:83], v[100:101]
	v_pk_fma_f32 v[80:81], v[136:137], v[80:81], v[108:109]
	v_pk_fma_f32 v[78:79], v[134:135], v[78:79], v[102:103]
	v_pk_fma_f32 v[76:77], v[132:133], v[76:77], v[110:111]
	v_pk_fma_f32 v[74:75], v[130:131], v[74:75], v[104:105]
	v_pk_fma_f32 v[72:73], v[128:129], v[72:73], v[112:113]
	v_pk_fma_f32 v[100:101], v[122:123], v[70:71], v[106:107]
	v_pk_fma_f32 v[92:93], v[120:121], v[68:69], v[92:93]
	v_cvt_pk_bf16_f32 v68, v80, v81
	v_cvt_pk_bf16_f32 v69, v82, v83
	v_cvt_pk_bf16_f32 v70, v76, v77
	v_cvt_pk_bf16_f32 v71, v78, v79
	v_cvt_pk_bf16_f32 v72, v72, v73
	v_cvt_pk_bf16_f32 v73, v74, v75
	v_cvt_pk_bf16_f32 v74, v92, v93
	v_cvt_pk_bf16_f32 v75, v100, v101
	global_store_dwordx4 v[96:97], v[68:71], off sc1
	global_store_dwordx4 v[96:97], v[72:75], off offset:256 sc1
	v_add_u32_e32 v68, 0x90, v166
	v_ashrrev_i32_e32 v69, 31, v68
	v_lshl_add_u64 v[80:81], s[24:25], 0, v[94:95]
	s_waitcnt vmcnt(3)
	v_lshlrev_b32_e32 v92, 16, v84
	v_and_b32_e32 v93, 0xffff0000, v84
	v_lshlrev_b32_e32 v84, 16, v85
	v_and_b32_e32 v85, 0xffff0000, v85
	v_lshlrev_b32_e32 v94, 16, v86
	v_and_b32_e32 v95, 0xffff0000, v86
	v_lshlrev_b32_e32 v86, 16, v87
	v_and_b32_e32 v87, 0xffff0000, v87
	v_lshlrev_b32_e32 v70, 2, v68
	v_lshlrev_b64 v[78:79], 11, v[68:69]
	s_waitcnt vmcnt(2)
	v_lshlrev_b32_e32 v96, 16, v88
	v_and_b32_e32 v97, 0xffff0000, v88
	v_lshlrev_b32_e32 v88, 16, v89
	v_and_b32_e32 v89, 0xffff0000, v89
	v_ashrrev_i32_e32 v71, 31, v70
	v_lshl_add_u64 v[72:73], v[164:165], 0, v[78:79]
	v_lshl_add_u64 v[80:81], v[80:81], 0, v[2:3]
	v_lshl_add_u64 v[82:83], v[70:71], 2, s[46:47]
	global_load_dwordx4 v[68:71], v[72:73], off
	s_nop 0
	global_load_dwordx4 v[72:75], v[72:73], off offset:256
	s_waitcnt vmcnt(4)
	v_add_f32_e32 v1, v218, v219
	v_fmamk_f32 v1, v1, 0x3b000000, v174
	v_mul_f32_e32 v76, 0x4f800000, v1
	v_cmp_gt_f32_e32 vcc, s61, v1
	v_and_b32_e32 v77, 0xffff0000, v90
	s_nop 0
	v_cndmask_b32_e32 v1, v1, v76, vcc
	v_sqrt_f32_e32 v98, v1
	v_lshlrev_b32_e32 v76, 16, v90
	v_lshlrev_b32_e32 v90, 16, v91
	v_and_b32_e32 v91, 0xffff0000, v91
	v_add_u32_e32 v99, -1, v98
	v_add_u32_e32 v100, 1, v98
	v_fma_f32 v101, -v99, v98, v1
	v_fma_f32 v102, -v100, v98, v1
	v_cmp_ge_f32_e64 s[6:7], 0, v101
	s_nop 1
	v_cndmask_b32_e64 v98, v98, v99, s[6:7]
	v_cmp_lt_f32_e64 s[6:7], 0, v102
	s_nop 1
	v_cndmask_b32_e64 v98, v98, v100, s[6:7]
	v_mul_f32_e32 v99, 0x37800000, v98
	v_cndmask_b32_e32 v98, v98, v99, vcc
	v_cmp_class_f32_e32 vcc, v1, v172
	s_nop 1
	v_cndmask_b32_e32 v1, v98, v1, vcc
	v_div_scale_f32 v98, s[6:7], v1, v1, 1.0
	v_rcp_f32_e32 v99, v98
	v_div_scale_f32 v100, vcc, 1.0, v1, 1.0
	v_fma_f32 v101, -v98, v99, 1.0
	v_fmac_f32_e32 v99, v101, v99
	v_mul_f32_e32 v101, v100, v99
	v_fma_f32 v102, -v98, v101, v100
	v_fmac_f32_e32 v101, v102, v99
	v_fma_f32 v98, -v98, v101, v100
	v_div_fmas_f32 v98, v98, v99, v101
	v_div_fixup_f32 v98, v98, v1, 1.0
	v_pk_mul_f32 v[64:65], v[64:65], v[98:99] op_sel_hi:[1,0]
	v_pk_mul_f32 v[66:67], v[66:67], v[98:99] op_sel_hi:[1,0]
	v_pk_mul_f32 v[60:61], v[60:61], v[98:99] op_sel_hi:[1,0]
	v_pk_mul_f32 v[62:63], v[62:63], v[98:99] op_sel_hi:[1,0]
	v_pk_mul_f32 v[56:57], v[56:57], v[98:99] op_sel_hi:[1,0]
	v_pk_mul_f32 v[58:59], v[58:59], v[98:99] op_sel_hi:[1,0]
	v_pk_mul_f32 v[52:53], v[52:53], v[98:99] op_sel_hi:[1,0]
	v_pk_mul_f32 v[54:55], v[54:55], v[98:99] op_sel_hi:[1,0]
	v_pk_fma_f32 v[66:67], v[138:139], v[66:67], v[84:85]
	v_pk_fma_f32 v[64:65], v[136:137], v[64:65], v[92:93]
	v_pk_fma_f32 v[62:63], v[134:135], v[62:63], v[86:87]
	v_pk_fma_f32 v[60:61], v[132:133], v[60:61], v[94:95]
	v_pk_fma_f32 v[58:59], v[130:131], v[58:59], v[88:89]
	v_pk_fma_f32 v[56:57], v[128:129], v[56:57], v[96:97]
	v_pk_fma_f32 v[84:85], v[122:123], v[54:55], v[90:91]
	v_pk_fma_f32 v[76:77], v[120:121], v[52:53], v[76:77]
	v_cvt_pk_bf16_f32 v52, v64, v65
	v_cvt_pk_bf16_f32 v53, v66, v67
	v_cvt_pk_bf16_f32 v54, v60, v61
	v_cvt_pk_bf16_f32 v55, v62, v63
	v_cvt_pk_bf16_f32 v56, v56, v57
	v_cvt_pk_bf16_f32 v57, v58, v59
	v_cvt_pk_bf16_f32 v58, v76, v77
	v_cvt_pk_bf16_f32 v59, v84, v85
	global_store_dwordx4 v[80:81], v[52:55], off sc1
	global_store_dwordx4 v[80:81], v[56:59], off offset:256 sc1
	v_add_u32_e32 v52, 0xa0, v166
	v_ashrrev_i32_e32 v53, 31, v52
	v_lshl_add_u64 v[64:65], s[24:25], 0, v[78:79]
	s_waitcnt vmcnt(3)
; __device__ __forceinline__ unsigned cvt_pk_bf16(float lo, float hi) { f32x2c_t v = {lo, hi}; bf16x2c_t b = __builtin_convertvector(v, bf16x2c_t); return __builtin_bit_cast(unsigned, b); }
; __device__ __forceinline__ f32x4 bf4_lo(u32x4 w) { return (f32x4){__uint_as_float(w.x << 16), __uint_as_float(w.x & 0xffff0000u), __uint_as_float(w.y << 16), __uint_as_float(w.y & 0xffff0000u)}; }
; __device__ __forceinline__ f32x4 bf4_hi(u32x4 w) { return (f32x4){__uint_as_float(w.z << 16), __uint_as_float(w.z & 0xffff0000u), __uint_as_float(w.w << 16), __uint_as_float(w.w & 0xffff0000u)}; }
;     __device__ __forceinline__ void operator()(const f32x4 (&acc)[2][2][4][2], const Unit& u, int wr, int wc, int fr, int fq) const {
;     ...
;         for (int ai = 0; ai < 2; ++ai)
; #pragma unroll
;             for (int m = 0; m < 4; ++m) { const int row = row0 + ai * HALF + m * 16; const size_t off = (size_t)row * 1024 + col0; float rs = 1.f; if constexpr (MIX) { const float* sp = rs2 + 4 * row + 2; rs = 1.0f / sqrtf((sp[0] + sp[1]) * (1.f / 512.f) + NEPS); }
; #pragma unroll
;                 for (int bj = 0; bj < 2; ++bj) { f32x4 x0, x1;
;                     if constexpr (XF32) { x0 = *(const f32x4*)((const float*)xin + off + bj * HALF); x1 = *(const f32x4*)((const float*)xin + off + bj * HALF + 4); }
;                     else { const u32x4 w = xw[ai][m][bj]; x0 = bf4_lo(w); x1 = bf4_hi(w); }
;                     const f32x4 o0 = x0 + gv[bj][0] * (acc[ai][bj][m][0] * rs), o1 = x1 + gv[bj][1] * (acc[ai][bj][m][1] * rs);
;                     u32x4 w; w.x = cvt_pk_bf16(o0[0], o0[1]); w.y = cvt_pk_bf16(o0[2], o0[3]); w.z = cvt_pk_bf16(o1[0], o1[1]); w.w = cvt_pk_bf16(o1[2], o1[3]);
;                     *(u32x4*)(xout + off + bj * HALF) = w; } }
	v_lshlrev_b32_e32 v76, 16, v68
	v_and_b32_e32 v77, 0xffff0000, v68
	v_lshlrev_b32_e32 v68, 16, v69
	v_and_b32_e32 v69, 0xffff0000, v69
	v_lshlrev_b32_e32 v78, 16, v70
	v_and_b32_e32 v79, 0xffff0000, v70
	v_lshlrev_b32_e32 v70, 16, v71
	v_and_b32_e32 v71, 0xffff0000, v71
	v_lshlrev_b32_e32 v54, 2, v52
	v_lshlrev_b64 v[62:63], 11, v[52:53]
	s_waitcnt vmcnt(2)
	v_lshlrev_b32_e32 v80, 16, v72
	v_and_b32_e32 v81, 0xffff0000, v72
	v_lshlrev_b32_e32 v72, 16, v73
	v_and_b32_e32 v73, 0xffff0000, v73
	v_ashrrev_i32_e32 v55, 31, v54
	v_lshl_add_u64 v[56:57], v[164:165], 0, v[62:63]
	v_lshl_add_u64 v[64:65], v[64:65], 0, v[2:3]
	v_lshl_add_u64 v[66:67], v[54:55], 2, s[46:47]
	global_load_dwordx4 v[52:55], v[56:57], off
	s_nop 0
	global_load_dwordx4 v[56:59], v[56:57], off offset:256
	s_waitcnt vmcnt(4)
	v_add_f32_e32 v1, v220, v221
	v_fmamk_f32 v1, v1, 0x3b000000, v174
	v_mul_f32_e32 v60, 0x4f800000, v1
	v_cmp_gt_f32_e32 vcc, s61, v1
	v_and_b32_e32 v61, 0xffff0000, v74
	s_nop 0
	v_cndmask_b32_e32 v1, v1, v60, vcc
	v_sqrt_f32_e32 v82, v1
	v_lshlrev_b32_e32 v60, 16, v74
	v_lshlrev_b32_e32 v74, 16, v75
	v_and_b32_e32 v75, 0xffff0000, v75
	v_add_u32_e32 v83, -1, v82
	v_add_u32_e32 v84, 1, v82
	v_fma_f32 v85, -v83, v82, v1
	v_fma_f32 v86, -v84, v82, v1
	v_cmp_ge_f32_e64 s[6:7], 0, v85
	s_nop 1
	v_cndmask_b32_e64 v82, v82, v83, s[6:7]
	v_cmp_lt_f32_e64 s[6:7], 0, v86
	s_nop 1
	v_cndmask_b32_e64 v82, v82, v84, s[6:7]
	v_mul_f32_e32 v83, 0x37800000, v82
	v_cndmask_b32_e32 v82, v82, v83, vcc
	v_cmp_class_f32_e32 vcc, v1, v172
	s_nop 1
	v_cndmask_b32_e32 v1, v82, v1, vcc
	v_div_scale_f32 v82, s[6:7], v1, v1, 1.0
	v_rcp_f32_e32 v83, v82
	v_div_scale_f32 v84, vcc, 1.0, v1, 1.0
	v_fma_f32 v85, -v82, v83, 1.0
	v_fmac_f32_e32 v83, v85, v83
	v_mul_f32_e32 v85, v84, v83
	v_fma_f32 v86, -v82, v85, v84
	v_fmac_f32_e32 v85, v86, v83
	v_fma_f32 v82, -v82, v85, v84
	v_div_fmas_f32 v82, v82, v83, v85
	v_div_fixup_f32 v82, v82, v1, 1.0
	v_pk_mul_f32 v[48:49], v[48:49], v[82:83] op_sel_hi:[1,0]
	v_pk_mul_f32 v[50:51], v[50:51], v[82:83] op_sel_hi:[1,0]
	v_pk_mul_f32 v[44:45], v[44:45], v[82:83] op_sel_hi:[1,0]
	v_pk_mul_f32 v[46:47], v[46:47], v[82:83] op_sel_hi:[1,0]
	v_pk_mul_f32 v[40:41], v[40:41], v[82:83] op_sel_hi:[1,0]
	v_pk_mul_f32 v[42:43], v[42:43], v[82:83] op_sel_hi:[1,0]
	v_pk_mul_f32 v[36:37], v[36:37], v[82:83] op_sel_hi:[1,0]
	v_pk_mul_f32 v[38:39], v[38:39], v[82:83] op_sel_hi:[1,0]
	v_pk_fma_f32 v[50:51], v[138:139], v[50:51], v[68:69]
	v_pk_fma_f32 v[48:49], v[136:137], v[48:49], v[76:77]
	v_pk_fma_f32 v[46:47], v[134:135], v[46:47], v[70:71]
	v_pk_fma_f32 v[44:45], v[132:133], v[44:45], v[78:79]
	v_pk_fma_f32 v[42:43], v[130:131], v[42:43], v[72:73]
	v_pk_fma_f32 v[40:41], v[128:129], v[40:41], v[80:81]
	v_pk_fma_f32 v[68:69], v[122:123], v[38:39], v[74:75]
	v_pk_fma_f32 v[60:61], v[120:121], v[36:37], v[60:61]
	v_cvt_pk_bf16_f32 v36, v48, v49
	v_cvt_pk_bf16_f32 v37, v50, v51
	v_cvt_pk_bf16_f32 v38, v44, v45
	v_cvt_pk_bf16_f32 v39, v46, v47
	v_cvt_pk_bf16_f32 v40, v40, v41
	v_cvt_pk_bf16_f32 v41, v42, v43
	v_cvt_pk_bf16_f32 v42, v60, v61
	v_cvt_pk_bf16_f32 v43, v68, v69
	global_store_dwordx4 v[64:65], v[36:39], off sc1
	global_store_dwordx4 v[64:65], v[40:43], off offset:256 sc1
	v_add_u32_e32 v36, 0xb0, v166
	v_ashrrev_i32_e32 v37, 31, v36
	v_lshl_add_u64 v[48:49], s[24:25], 0, v[62:63]
	s_waitcnt vmcnt(3)
	v_lshlrev_b32_e32 v60, 16, v52
	v_and_b32_e32 v61, 0xffff0000, v52
	v_lshlrev_b32_e32 v52, 16, v53
	v_and_b32_e32 v53, 0xffff0000, v53
	v_lshlrev_b32_e32 v62, 16, v54
	v_and_b32_e32 v63, 0xffff0000, v54
	v_lshlrev_b32_e32 v54, 16, v55
	v_and_b32_e32 v55, 0xffff0000, v55
	v_lshlrev_b32_e32 v38, 2, v36
	v_lshlrev_b64 v[46:47], 11, v[36:37]
	s_waitcnt vmcnt(2)
	v_lshlrev_b32_e32 v64, 16, v56
	v_and_b32_e32 v65, 0xffff0000, v56
	v_lshlrev_b32_e32 v56, 16, v57
	v_and_b32_e32 v57, 0xffff0000, v57
	v_ashrrev_i32_e32 v39, 31, v38
	v_lshl_add_u64 v[40:41], v[164:165], 0, v[46:47]
	v_lshl_add_u64 v[48:49], v[48:49], 0, v[2:3]
	v_lshl_add_u64 v[50:51], v[38:39], 2, s[46:47]
	global_load_dwordx4 v[36:39], v[40:41], off
	s_nop 0
	global_load_dwordx4 v[40:43], v[40:41], off offset:256
	s_waitcnt vmcnt(4)
; __device__ __forceinline__ unsigned cvt_pk_bf16(float lo, float hi) { f32x2c_t v = {lo, hi}; bf16x2c_t b = __builtin_convertvector(v, bf16x2c_t); return __builtin_bit_cast(unsigned, b); }
; __device__ __forceinline__ f32x4 bf4_lo(u32x4 w) { return (f32x4){__uint_as_float(w.x << 16), __uint_as_float(w.x & 0xffff0000u), __uint_as_float(w.y << 16), __uint_as_float(w.y & 0xffff0000u)}; }
; __device__ __forceinline__ f32x4 bf4_hi(u32x4 w) { return (f32x4){__uint_as_float(w.z << 16), __uint_as_float(w.z & 0xffff0000u), __uint_as_float(w.w << 16), __uint_as_float(w.w & 0xffff0000u)}; }
;     __device__ __forceinline__ void operator()(const f32x4 (&acc)[2][2][4][2], const Unit& u, int wr, int wc, int fr, int fq) const {
;     ...
;         for (int ai = 0; ai < 2; ++ai)
; #pragma unroll
;             for (int m = 0; m < 4; ++m) { const int row = row0 + ai * HALF + m * 16; const size_t off = (size_t)row * 1024 + col0; float rs = 1.f; if constexpr (MIX) { const float* sp = rs2 + 4 * row + 2; rs = 1.0f / sqrtf((sp[0] + sp[1]) * (1.f / 512.f) + NEPS); }
; #pragma unroll
;                 for (int bj = 0; bj < 2; ++bj) { f32x4 x0, x1;
;                     if constexpr (XF32) { x0 = *(const f32x4*)((const float*)xin + off + bj * HALF); x1 = *(const f32x4*)((const float*)xin + off + bj * HALF + 4); }
;                     else { const u32x4 w = xw[ai][m][bj]; x0 = bf4_lo(w); x1 = bf4_hi(w); }
;                     const f32x4 o0 = x0 + gv[bj][0] * (acc[ai][bj][m][0] * rs), o1 = x1 + gv[bj][1] * (acc[ai][bj][m][1] * rs);
;                     u32x4 w; w.x = cvt_pk_bf16(o0[0], o0[1]); w.y = cvt_pk_bf16(o0[2], o0[3]); w.z = cvt_pk_bf16(o1[0], o1[1]); w.w = cvt_pk_bf16(o1[2], o1[3]);
;                     *(u32x4*)(xout + off + bj * HALF) = w; } }
	v_add_f32_e32 v1, v222, v223
	v_fmamk_f32 v1, v1, 0x3b000000, v174
	v_mul_f32_e32 v44, 0x4f800000, v1
	v_cmp_gt_f32_e32 vcc, s61, v1
	v_and_b32_e32 v45, 0xffff0000, v58
	s_nop 0
	v_cndmask_b32_e32 v1, v1, v44, vcc
	v_sqrt_f32_e32 v66, v1
	v_lshlrev_b32_e32 v44, 16, v58
	v_lshlrev_b32_e32 v58, 16, v59
	v_and_b32_e32 v59, 0xffff0000, v59
	v_add_u32_e32 v67, -1, v66
	v_add_u32_e32 v68, 1, v66
	v_fma_f32 v69, -v67, v66, v1
	v_fma_f32 v70, -v68, v66, v1
	v_cmp_ge_f32_e64 s[6:7], 0, v69
	s_nop 1
	v_cndmask_b32_e64 v66, v66, v67, s[6:7]
	v_cmp_lt_f32_e64 s[6:7], 0, v70
	s_nop 1
	v_cndmask_b32_e64 v66, v66, v68, s[6:7]
	v_mul_f32_e32 v67, 0x37800000, v66
	v_cndmask_b32_e32 v66, v66, v67, vcc
	v_cmp_class_f32_e32 vcc, v1, v172
	s_nop 1
	v_cndmask_b32_e32 v1, v66, v1, vcc
	v_div_scale_f32 v66, s[6:7], v1, v1, 1.0
	v_rcp_f32_e32 v67, v66
	v_div_scale_f32 v68, vcc, 1.0, v1, 1.0
	v_fma_f32 v69, -v66, v67, 1.0
	v_fmac_f32_e32 v67, v69, v67
	v_mul_f32_e32 v69, v68, v67
	v_fma_f32 v70, -v66, v69, v68
	v_fmac_f32_e32 v69, v70, v67
	v_fma_f32 v66, -v66, v69, v68
	v_div_fmas_f32 v66, v66, v67, v69
	v_div_fixup_f32 v66, v66, v1, 1.0
	v_pk_mul_f32 v[32:33], v[32:33], v[66:67] op_sel_hi:[1,0]
	v_pk_mul_f32 v[34:35], v[34:35], v[66:67] op_sel_hi:[1,0]
	v_pk_mul_f32 v[28:29], v[28:29], v[66:67] op_sel_hi:[1,0]
	v_pk_mul_f32 v[30:31], v[30:31], v[66:67] op_sel_hi:[1,0]
	v_pk_mul_f32 v[24:25], v[24:25], v[66:67] op_sel_hi:[1,0]
	v_pk_mul_f32 v[26:27], v[26:27], v[66:67] op_sel_hi:[1,0]
	v_pk_mul_f32 v[20:21], v[20:21], v[66:67] op_sel_hi:[1,0]
	v_pk_mul_f32 v[22:23], v[22:23], v[66:67] op_sel_hi:[1,0]
	v_pk_fma_f32 v[34:35], v[138:139], v[34:35], v[52:53]
	v_pk_fma_f32 v[32:33], v[136:137], v[32:33], v[60:61]
	v_pk_fma_f32 v[30:31], v[134:135], v[30:31], v[54:55]
	v_pk_fma_f32 v[28:29], v[132:133], v[28:29], v[62:63]
	v_pk_fma_f32 v[26:27], v[130:131], v[26:27], v[56:57]
	v_pk_fma_f32 v[24:25], v[128:129], v[24:25], v[64:65]
	v_pk_fma_f32 v[52:53], v[122:123], v[22:23], v[58:59]
	v_pk_fma_f32 v[44:45], v[120:121], v[20:21], v[44:45]
	v_cvt_pk_bf16_f32 v20, v32, v33
	v_cvt_pk_bf16_f32 v21, v34, v35
	v_cvt_pk_bf16_f32 v22, v28, v29
	v_cvt_pk_bf16_f32 v23, v30, v31
	v_cvt_pk_bf16_f32 v24, v24, v25
	v_cvt_pk_bf16_f32 v25, v26, v27
	v_cvt_pk_bf16_f32 v26, v44, v45
	v_cvt_pk_bf16_f32 v27, v52, v53
	global_store_dwordx4 v[48:49], v[20:23], off sc1
	global_store_dwordx4 v[48:49], v[24:27], off offset:256 sc1
	v_lshl_add_u64 v[22:23], s[24:25], 0, v[46:47]
	v_lshl_add_u64 v[22:23], v[22:23], 0, v[2:3]
	s_waitcnt vmcnt(3)
	v_lshlrev_b32_e32 v2, 16, v36
	v_and_b32_e32 v3, 0xffff0000, v36
	v_lshlrev_b32_e32 v24, 16, v37
	v_and_b32_e32 v25, 0xffff0000, v37
	v_lshlrev_b32_e32 v26, 16, v38
	v_and_b32_e32 v27, 0xffff0000, v38
	v_lshlrev_b32_e32 v28, 16, v39
	v_and_b32_e32 v29, 0xffff0000, v39
	s_waitcnt vmcnt(2)
	v_lshlrev_b32_e32 v30, 16, v40
	v_and_b32_e32 v31, 0xffff0000, v40
	v_lshlrev_b32_e32 v32, 16, v41
	v_and_b32_e32 v33, 0xffff0000, v41
	v_lshlrev_b32_e32 v34, 16, v43
	s_waitcnt vmcnt(2)
	v_add_f32_e32 v1, v224, v225
	v_fmamk_f32 v1, v1, 0x3b000000, v174
	v_mul_f32_e32 v20, 0x4f800000, v1
	v_cmp_gt_f32_e32 vcc, s61, v1
	v_and_b32_e32 v21, 0xffff0000, v42
	s_nop 0
	v_cndmask_b32_e32 v1, v1, v20, vcc
	v_sqrt_f32_e32 v35, v1
	v_lshlrev_b32_e32 v20, 16, v42
	v_add_u32_e32 v36, -1, v35
	v_add_u32_e32 v37, 1, v35
	v_fma_f32 v38, -v36, v35, v1
	v_fma_f32 v39, -v37, v35, v1
	v_cmp_ge_f32_e64 s[6:7], 0, v38
	s_nop 1
	v_cndmask_b32_e64 v35, v35, v36, s[6:7]
	v_cmp_lt_f32_e64 s[6:7], 0, v39
	s_nop 1
	v_cndmask_b32_e64 v35, v35, v37, s[6:7]
	v_mul_f32_e32 v36, 0x37800000, v35
	v_cndmask_b32_e32 v35, v35, v36, vcc
	v_cmp_class_f32_e32 vcc, v1, v172
	s_nop 1
	v_cndmask_b32_e32 v1, v35, v1, vcc
	v_div_scale_f32 v36, s[6:7], v1, v1, 1.0
	v_rcp_f32_e32 v37, v36
	v_div_scale_f32 v38, vcc, 1.0, v1, 1.0
	v_and_b32_e32 v35, 0xffff0000, v43
	v_fma_f32 v39, -v36, v37, 1.0
	v_fmac_f32_e32 v37, v39, v37
	v_mul_f32_e32 v39, v38, v37
	v_fma_f32 v40, -v36, v39, v38
	v_fmac_f32_e32 v39, v40, v37
	v_fma_f32 v36, -v36, v39, v38
	v_div_fmas_f32 v36, v36, v37, v39
	v_div_fixup_f32 v36, v36, v1, 1.0
	v_pk_mul_f32 v[16:17], v[16:17], v[36:37] op_sel_hi:[1,0]
	v_pk_mul_f32 v[18:19], v[18:19], v[36:37] op_sel_hi:[1,0]
	v_pk_mul_f32 v[12:13], v[12:13], v[36:37] op_sel_hi:[1,0]
	v_pk_mul_f32 v[14:15], v[14:15], v[36:37] op_sel_hi:[1,0]
	v_pk_mul_f32 v[8:9], v[8:9], v[36:37] op_sel_hi:[1,0]
	v_pk_mul_f32 v[10:11], v[10:11], v[36:37] op_sel_hi:[1,0]
	v_pk_mul_f32 v[4:5], v[4:5], v[36:37] op_sel_hi:[1,0]
	v_pk_mul_f32 v[6:7], v[6:7], v[36:37] op_sel_hi:[1,0]
	v_pk_fma_f32 v[18:19], v[138:139], v[18:19], v[24:25]
	v_pk_fma_f32 v[2:3], v[136:137], v[16:17], v[2:3]
	v_pk_fma_f32 v[14:15], v[134:135], v[14:15], v[28:29]
	v_pk_fma_f32 v[12:13], v[132:133], v[12:13], v[26:27]
	s_andn2_b64 vcc, exec, s[0:1]
	v_pk_fma_f32 v[10:11], v[130:131], v[10:11], v[32:33]
	v_pk_fma_f32 v[8:9], v[128:129], v[8:9], v[30:31]
	v_pk_fma_f32 v[16:17], v[122:123], v[6:7], v[34:35]
	v_pk_fma_f32 v[20:21], v[120:121], v[4:5], v[20:21]
	v_cvt_pk_bf16_f32 v2, v2, v3
	v_cvt_pk_bf16_f32 v3, v18, v19
	v_cvt_pk_bf16_f32 v4, v12, v13
	v_cvt_pk_bf16_f32 v5, v14, v15
	s_mov_b64 s[0:1], -1
	v_cvt_pk_bf16_f32 v6, v8, v9
	v_cvt_pk_bf16_f32 v7, v10, v11
	v_cvt_pk_bf16_f32 v8, v20, v21
	v_cvt_pk_bf16_f32 v9, v16, v17
	global_store_dwordx4 v[22:23], v[2:5], off sc1
	global_store_dwordx4 v[22:23], v[6:9], off offset:256 sc1
	s_cbranch_vccnz .LBB0_890
	s_andn2_b64 vcc, exec, s[16:17]
	s_cbranch_vccnz .LBB0_889
	s_barrier
	s_branch .LBB0_889
